# v20 + spare-workgroup GEMM (gate tiles) epilogue stores write-through (sc0 sc1), like the P1 epilogue
# speedup vs baseline: 1.0063x; 1.0063x over previous
.LBB0_353:
	s_add_u32 s14, s12, 0xfffc0080
	s_addc_u32 s15, s13, -1
	s_add_i32 s39, 0, 0x10000
	v_add_u32_e32 v140, s39, v143
	ds_read_b128 v[146:149], v140
	ds_read_b128 v[150:153], v140 offset:1024
	ds_read_b128 v[168:171], v140 offset:2048
	ds_read_b128 v[172:175], v140 offset:3072
	s_cmp_eq_u32 s38, 12
	s_cselect_b32 s17, s5, s15
	s_cselect_b32 s16, s34, s14
	s_cselect_b32 s15, s3, s37
	s_cselect_b32 s14, s35, s36
	v_lshl_add_u64 v[140:141], s[12:13], 0, v[136:137]
	s_add_i32 m0, s22, 0xc000
	ds_read_b128 v[176:179], v145
	ds_read_b128 v[180:183], v145 offset:1024
	ds_read_b128 v[184:187], v145 offset:2048
	ds_read_b128 v[188:191], v145 offset:3072
	ds_read_b128 v[192:195], v145 offset:4096
	ds_read_b128 v[196:199], v145 offset:5120
	ds_read_b128 v[200:203], v145 offset:6144
	ds_read_b128 v[204:207], v145 offset:7168
	global_load_lds_dwordx4 v[140:141], off
	v_lshl_add_u64 v[140:141], s[12:13], 0, v[138:139]
	s_add_i32 m0, s22, 0xe000
	s_nop 0
	global_load_lds_dwordx4 v[140:141], off
	s_waitcnt lgkmcnt(8)
	s_barrier
	s_waitcnt lgkmcnt(0)
	s_setprio 1
	s_waitcnt lgkmcnt(0)
	v_mfma_f32_16x16x32_bf16 v[128:131], v[146:149], v[176:179], v[128:131]
	v_mfma_f32_16x16x32_bf16 v[124:127], v[168:171], v[176:179], v[124:127]
	v_mfma_f32_16x16x32_bf16 v[116:119], v[146:149], v[184:187], v[116:119]
	v_mfma_f32_16x16x32_bf16 v[108:111], v[168:171], v[184:187], v[108:111]
	v_mfma_f32_16x16x32_bf16 v[100:103], v[146:149], v[192:195], v[100:103]
	v_mfma_f32_16x16x32_bf16 v[92:95], v[168:171], v[192:195], v[92:95]
	v_mfma_f32_16x16x32_bf16 v[84:87], v[146:149], v[200:203], v[84:87]
	v_mfma_f32_16x16x32_bf16 v[76:79], v[168:171], v[200:203], v[76:79]
	v_mfma_f32_16x16x32_bf16 v[128:131], v[150:153], v[180:183], v[128:131]
	v_mfma_f32_16x16x32_bf16 v[124:127], v[172:175], v[180:183], v[124:127]
	v_mfma_f32_16x16x32_bf16 v[116:119], v[150:153], v[188:191], v[116:119]
	v_mfma_f32_16x16x32_bf16 v[108:111], v[172:175], v[188:191], v[108:111]
	v_mfma_f32_16x16x32_bf16 v[100:103], v[150:153], v[196:199], v[100:103]
	v_mfma_f32_16x16x32_bf16 v[92:95], v[172:175], v[196:199], v[92:95]
	v_mfma_f32_16x16x32_bf16 v[84:87], v[150:153], v[204:207], v[84:87]
	v_mfma_f32_16x16x32_bf16 v[76:79], v[172:175], v[204:207], v[76:79]
	s_setprio 0
	s_barrier
	s_add_i32 s42, 0, 0x14000
	v_add_u32_e32 v140, s42, v143
	s_add_i32 s39, s39, s21
	ds_read_b128 v[208:211], v140
	ds_read_b128 v[212:215], v140 offset:1024
	ds_read_b128 v[216:219], v140 offset:2048
	ds_read_b128 v[220:223], v140 offset:3072
	v_lshl_add_u64 v[140:141], s[14:15], 0, v[2:3]
	s_mov_b32 m0, s39
	v_lshl_add_u64 v[154:155], s[14:15], 0, v[0:1]
	global_load_lds_dwordx4 v[140:141], off
	s_add_i32 m0, s39, 0x2000
	s_nop 0
	global_load_lds_dwordx4 v[154:155], off
	s_barrier
	s_waitcnt lgkmcnt(0)
	s_setprio 1
	s_waitcnt lgkmcnt(0)
	v_mfma_f32_16x16x32_bf16 v[120:123], v[208:211], v[176:179], v[120:123]
	v_mfma_f32_16x16x32_bf16 v[112:115], v[216:219], v[176:179], v[112:115]
	v_mfma_f32_16x16x32_bf16 v[104:107], v[208:211], v[184:187], v[104:107]
	v_mfma_f32_16x16x32_bf16 v[96:99], v[216:219], v[184:187], v[96:99]
	v_mfma_f32_16x16x32_bf16 v[88:91], v[208:211], v[192:195], v[88:91]
	v_mfma_f32_16x16x32_bf16 v[80:83], v[216:219], v[192:195], v[80:83]
	v_mfma_f32_16x16x32_bf16 v[72:75], v[208:211], v[200:203], v[72:75]
	v_mfma_f32_16x16x32_bf16 v[68:71], v[216:219], v[200:203], v[68:71]
	v_mfma_f32_16x16x32_bf16 v[120:123], v[212:215], v[180:183], v[120:123]
	v_mfma_f32_16x16x32_bf16 v[112:115], v[220:223], v[180:183], v[112:115]
	v_mfma_f32_16x16x32_bf16 v[104:107], v[212:215], v[188:191], v[104:107]
	v_mfma_f32_16x16x32_bf16 v[96:99], v[220:223], v[188:191], v[96:99]
	v_mfma_f32_16x16x32_bf16 v[88:91], v[212:215], v[196:199], v[88:91]
	v_mfma_f32_16x16x32_bf16 v[80:83], v[220:223], v[196:199], v[80:83]
	v_mfma_f32_16x16x32_bf16 v[72:75], v[212:215], v[204:207], v[72:75]
	v_mfma_f32_16x16x32_bf16 v[68:71], v[220:223], v[204:207], v[68:71]
	s_setprio 0
	s_mov_b32 m0, s22
	v_lshl_add_u64 v[224:225], s[16:17], 0, v[134:135]
	s_barrier
	ds_read_b128 v[176:179], v145 offset:16384
	ds_read_b128 v[180:183], v145 offset:17408
	ds_read_b128 v[184:187], v145 offset:18432
	ds_read_b128 v[188:191], v145 offset:19456
	ds_read_b128 v[192:195], v145 offset:20480
	ds_read_b128 v[196:199], v145 offset:21504
	ds_read_b128 v[200:203], v145 offset:22528
	ds_read_b128 v[204:207], v145 offset:23552
	global_load_lds_dwordx4 v[224:225], off
	v_lshl_add_u64 v[226:227], s[16:17], 0, v[132:133]
	s_mov_b32 m0, s23
	s_nop 0
	global_load_lds_dwordx4 v[226:227], off
	s_barrier
	s_waitcnt lgkmcnt(0)
	s_setprio 1
	s_waitcnt lgkmcnt(0)
	v_mfma_f32_16x16x32_bf16 v[64:67], v[146:149], v[176:179], v[64:67]
	v_mfma_f32_16x16x32_bf16 v[60:63], v[168:171], v[176:179], v[60:63]
	v_mfma_f32_16x16x32_bf16 v[52:55], v[146:149], v[184:187], v[52:55]
	v_mfma_f32_16x16x32_bf16 v[44:47], v[168:171], v[184:187], v[44:47]
	v_mfma_f32_16x16x32_bf16 v[36:39], v[146:149], v[192:195], v[36:39]
	v_mfma_f32_16x16x32_bf16 v[28:31], v[168:171], v[192:195], v[28:31]
	v_mfma_f32_16x16x32_bf16 v[20:23], v[146:149], v[200:203], v[20:23]
	v_mfma_f32_16x16x32_bf16 v[12:15], v[168:171], v[200:203], v[12:15]
	v_mfma_f32_16x16x32_bf16 v[64:67], v[150:153], v[180:183], v[64:67]
	v_mfma_f32_16x16x32_bf16 v[60:63], v[172:175], v[180:183], v[60:63]
	v_mfma_f32_16x16x32_bf16 v[52:55], v[150:153], v[188:191], v[52:55]
	v_mfma_f32_16x16x32_bf16 v[44:47], v[172:175], v[188:191], v[44:47]
	v_mfma_f32_16x16x32_bf16 v[36:39], v[150:153], v[196:199], v[36:39]
	v_mfma_f32_16x16x32_bf16 v[28:31], v[172:175], v[196:199], v[28:31]
	v_mfma_f32_16x16x32_bf16 v[20:23], v[150:153], v[204:207], v[20:23]
	v_mfma_f32_16x16x32_bf16 v[12:15], v[172:175], v[204:207], v[12:15]
	s_setprio 0
	s_barrier
	s_add_u32 s40, s14, 0x40000
	s_addc_u32 s41, s15, 0
	s_add_i32 s39, s42, s21
	v_lshl_add_u64 v[146:147], s[40:41], 0, v[2:3]
	s_mov_b32 m0, s39
	s_nop 0
	global_load_lds_dwordx4 v[146:147], off
	v_lshl_add_u64 v[146:147], s[40:41], 0, v[0:1]
	s_add_i32 m0, s39, 0x2000
	s_nop 0
	global_load_lds_dwordx4 v[146:147], off
	s_waitcnt vmcnt(6)
	s_barrier
	s_setprio 1
	v_mfma_f32_16x16x32_bf16 v[56:59], v[208:211], v[176:179], v[56:59]
	v_mfma_f32_16x16x32_bf16 v[48:51], v[216:219], v[176:179], v[48:51]
	v_mfma_f32_16x16x32_bf16 v[40:43], v[208:211], v[184:187], v[40:43]
	v_mfma_f32_16x16x32_bf16 v[32:35], v[216:219], v[184:187], v[32:35]
	v_mfma_f32_16x16x32_bf16 v[24:27], v[208:211], v[192:195], v[24:27]
	v_mfma_f32_16x16x32_bf16 v[16:19], v[216:219], v[192:195], v[16:19]
	v_mfma_f32_16x16x32_bf16 v[8:11], v[208:211], v[200:203], v[8:11]
	v_mfma_f32_16x16x32_bf16 v[4:7], v[216:219], v[200:203], v[4:7]
	v_mfma_f32_16x16x32_bf16 v[56:59], v[212:215], v[180:183], v[56:59]
	v_mfma_f32_16x16x32_bf16 v[48:51], v[220:223], v[180:183], v[48:51]
	v_mfma_f32_16x16x32_bf16 v[40:43], v[212:215], v[188:191], v[40:43]
	v_mfma_f32_16x16x32_bf16 v[32:35], v[220:223], v[188:191], v[32:35]
	v_mfma_f32_16x16x32_bf16 v[24:27], v[212:215], v[196:199], v[24:27]
	v_mfma_f32_16x16x32_bf16 v[16:19], v[220:223], v[196:199], v[16:19]
	v_mfma_f32_16x16x32_bf16 v[8:11], v[212:215], v[204:207], v[8:11]
	v_mfma_f32_16x16x32_bf16 v[4:7], v[220:223], v[204:207], v[4:7]
	s_setprio 0
	s_add_i32 s39, 0, 0x18000
	v_add_u32_e32 v161, s39, v143
	s_barrier
	ds_read_b128 v[146:149], v161
	ds_read_b128 v[150:153], v161 offset:1024
	ds_read_b128 v[168:171], v161 offset:2048
	ds_read_b128 v[172:175], v161 offset:3072
	s_add_u32 s16, s16, 0x40000
	s_addc_u32 s17, s17, 0
	s_mov_b32 m0, s24
	v_lshl_add_u64 v[208:209], s[16:17], 0, v[134:135]
	ds_read_b128 v[176:179], v145 offset:32768
	ds_read_b128 v[180:183], v145 offset:33792
	ds_read_b128 v[184:187], v145 offset:34816
	ds_read_b128 v[188:191], v145 offset:35840
	ds_read_b128 v[192:195], v145 offset:36864
	ds_read_b128 v[196:199], v145 offset:37888
	ds_read_b128 v[200:203], v145 offset:38912
	ds_read_b128 v[204:207], v145 offset:39936
	global_load_lds_dwordx4 v[208:209], off
	v_lshl_add_u64 v[208:209], s[16:17], 0, v[132:133]
	s_mov_b32 m0, s25
	s_nop 0
	global_load_lds_dwordx4 v[208:209], off
	s_waitcnt lgkmcnt(8)
	s_barrier
	s_waitcnt lgkmcnt(0)
	s_setprio 1
	s_waitcnt lgkmcnt(0)
	v_mfma_f32_16x16x32_bf16 v[128:131], v[146:149], v[176:179], v[128:131]
	v_mfma_f32_16x16x32_bf16 v[124:127], v[168:171], v[176:179], v[124:127]
	v_mfma_f32_16x16x32_bf16 v[116:119], v[146:149], v[184:187], v[116:119]
	v_mfma_f32_16x16x32_bf16 v[108:111], v[168:171], v[184:187], v[108:111]
	v_mfma_f32_16x16x32_bf16 v[100:103], v[146:149], v[192:195], v[100:103]
	v_mfma_f32_16x16x32_bf16 v[92:95], v[168:171], v[192:195], v[92:95]
	v_mfma_f32_16x16x32_bf16 v[84:87], v[146:149], v[200:203], v[84:87]
	v_mfma_f32_16x16x32_bf16 v[76:79], v[168:171], v[200:203], v[76:79]
	v_mfma_f32_16x16x32_bf16 v[128:131], v[150:153], v[180:183], v[128:131]
	v_mfma_f32_16x16x32_bf16 v[124:127], v[172:175], v[180:183], v[124:127]
	v_mfma_f32_16x16x32_bf16 v[116:119], v[150:153], v[188:191], v[116:119]
	v_mfma_f32_16x16x32_bf16 v[108:111], v[172:175], v[188:191], v[108:111]
	v_mfma_f32_16x16x32_bf16 v[100:103], v[150:153], v[196:199], v[100:103]
	v_mfma_f32_16x16x32_bf16 v[92:95], v[172:175], v[196:199], v[92:95]
	v_mfma_f32_16x16x32_bf16 v[84:87], v[150:153], v[204:207], v[84:87]
	v_mfma_f32_16x16x32_bf16 v[76:79], v[172:175], v[204:207], v[76:79]
	s_setprio 0
	s_barrier
	s_add_i32 s16, 0, 0x1c000
	s_add_i32 s17, s39, s21
	v_add_u32_e32 v161, s16, v143
	v_lshl_add_u64 v[140:141], v[140:141], 0, s[94:95]
	s_mov_b32 m0, s17
	ds_read_b128 v[208:211], v161
	ds_read_b128 v[212:215], v161 offset:1024
	ds_read_b128 v[216:219], v161 offset:2048
	ds_read_b128 v[220:223], v161 offset:3072
	global_load_lds_dwordx4 v[140:141], off
	v_lshl_add_u64 v[140:141], v[154:155], 0, s[94:95]
	s_add_i32 m0, s17, 0x2000
	s_nop 0
	global_load_lds_dwordx4 v[140:141], off
	s_barrier
	s_waitcnt lgkmcnt(0)
	s_setprio 1
	s_waitcnt lgkmcnt(0)
	v_mfma_f32_16x16x32_bf16 v[120:123], v[208:211], v[176:179], v[120:123]
	v_mfma_f32_16x16x32_bf16 v[112:115], v[216:219], v[176:179], v[112:115]
	v_mfma_f32_16x16x32_bf16 v[104:107], v[208:211], v[184:187], v[104:107]
	v_mfma_f32_16x16x32_bf16 v[96:99], v[216:219], v[184:187], v[96:99]
	v_mfma_f32_16x16x32_bf16 v[88:91], v[208:211], v[192:195], v[88:91]
	v_mfma_f32_16x16x32_bf16 v[80:83], v[216:219], v[192:195], v[80:83]
	v_mfma_f32_16x16x32_bf16 v[72:75], v[208:211], v[200:203], v[72:75]
	v_mfma_f32_16x16x32_bf16 v[68:71], v[216:219], v[200:203], v[68:71]
	v_mfma_f32_16x16x32_bf16 v[120:123], v[212:215], v[180:183], v[120:123]
	v_mfma_f32_16x16x32_bf16 v[112:115], v[220:223], v[180:183], v[112:115]
	v_mfma_f32_16x16x32_bf16 v[104:107], v[212:215], v[188:191], v[104:107]
	v_mfma_f32_16x16x32_bf16 v[96:99], v[220:223], v[188:191], v[96:99]
	v_mfma_f32_16x16x32_bf16 v[88:91], v[212:215], v[196:199], v[88:91]
	v_mfma_f32_16x16x32_bf16 v[80:83], v[220:223], v[196:199], v[80:83]
	v_mfma_f32_16x16x32_bf16 v[72:75], v[212:215], v[204:207], v[72:75]
	v_mfma_f32_16x16x32_bf16 v[68:71], v[220:223], v[204:207], v[68:71]
	s_setprio 0
	s_mov_b32 m0, s27
	v_lshl_add_u64 v[140:141], v[224:225], 0, s[94:95]
	s_barrier
	ds_read_b128 v[176:179], v145 offset:49152
	ds_read_b128 v[180:183], v145 offset:50176
	ds_read_b128 v[184:187], v145 offset:51200
	ds_read_b128 v[188:191], v145 offset:52224
	ds_read_b128 v[192:195], v145 offset:53248
	ds_read_b128 v[196:199], v145 offset:54272
	ds_read_b128 v[200:203], v145 offset:55296
	ds_read_b128 v[204:207], v145 offset:56320
	global_load_lds_dwordx4 v[140:141], off
	v_lshl_add_u64 v[140:141], v[226:227], 0, s[94:95]
	s_mov_b32 m0, s28
	s_nop 0
	global_load_lds_dwordx4 v[140:141], off
	s_barrier
	s_waitcnt lgkmcnt(0)
	s_setprio 1
	s_waitcnt lgkmcnt(0)
	v_mfma_f32_16x16x32_bf16 v[64:67], v[146:149], v[176:179], v[64:67]
	v_mfma_f32_16x16x32_bf16 v[60:63], v[168:171], v[176:179], v[60:63]
	v_mfma_f32_16x16x32_bf16 v[52:55], v[146:149], v[184:187], v[52:55]
	v_mfma_f32_16x16x32_bf16 v[44:47], v[168:171], v[184:187], v[44:47]
	v_mfma_f32_16x16x32_bf16 v[36:39], v[146:149], v[192:195], v[36:39]
	v_mfma_f32_16x16x32_bf16 v[28:31], v[168:171], v[192:195], v[28:31]
	v_mfma_f32_16x16x32_bf16 v[20:23], v[146:149], v[200:203], v[20:23]
	v_mfma_f32_16x16x32_bf16 v[12:15], v[168:171], v[200:203], v[12:15]
	v_mfma_f32_16x16x32_bf16 v[64:67], v[150:153], v[180:183], v[64:67]
	v_mfma_f32_16x16x32_bf16 v[60:63], v[172:175], v[180:183], v[60:63]
	v_mfma_f32_16x16x32_bf16 v[52:55], v[150:153], v[188:191], v[52:55]
	v_mfma_f32_16x16x32_bf16 v[44:47], v[172:175], v[188:191], v[44:47]
	v_mfma_f32_16x16x32_bf16 v[36:39], v[150:153], v[196:199], v[36:39]
	v_mfma_f32_16x16x32_bf16 v[28:31], v[172:175], v[196:199], v[28:31]
	v_mfma_f32_16x16x32_bf16 v[20:23], v[150:153], v[204:207], v[20:23]
	v_mfma_f32_16x16x32_bf16 v[12:15], v[172:175], v[204:207], v[12:15]
	s_setprio 0
	s_barrier
	s_add_u32 s14, s14, 0x40080
	s_addc_u32 s15, s15, 0
	s_add_i32 s16, s16, s21
	v_lshl_add_u64 v[140:141], s[14:15], 0, v[2:3]
	s_mov_b32 m0, s16
	s_nop 0
	global_load_lds_dwordx4 v[140:141], off
	v_lshl_add_u64 v[140:141], s[14:15], 0, v[0:1]
	s_add_i32 m0, s16, 0x2000
	s_nop 0
	global_load_lds_dwordx4 v[140:141], off
	s_waitcnt vmcnt(6)
	s_barrier
	s_setprio 1
	v_mfma_f32_16x16x32_bf16 v[56:59], v[208:211], v[176:179], v[56:59]
	v_mfma_f32_16x16x32_bf16 v[48:51], v[216:219], v[176:179], v[48:51]
	v_mfma_f32_16x16x32_bf16 v[40:43], v[208:211], v[184:187], v[40:43]
	v_mfma_f32_16x16x32_bf16 v[32:35], v[216:219], v[184:187], v[32:35]
	v_mfma_f32_16x16x32_bf16 v[24:27], v[208:211], v[192:195], v[24:27]
	v_mfma_f32_16x16x32_bf16 v[16:19], v[216:219], v[192:195], v[16:19]
	v_mfma_f32_16x16x32_bf16 v[8:11], v[208:211], v[200:203], v[8:11]
	v_mfma_f32_16x16x32_bf16 v[4:7], v[216:219], v[200:203], v[4:7]
	v_mfma_f32_16x16x32_bf16 v[56:59], v[212:215], v[180:183], v[56:59]
	v_mfma_f32_16x16x32_bf16 v[48:51], v[220:223], v[180:183], v[48:51]
	v_mfma_f32_16x16x32_bf16 v[40:43], v[212:215], v[188:191], v[40:43]
	v_mfma_f32_16x16x32_bf16 v[32:35], v[220:223], v[188:191], v[32:35]
	v_mfma_f32_16x16x32_bf16 v[24:27], v[212:215], v[196:199], v[24:27]
	v_mfma_f32_16x16x32_bf16 v[16:19], v[220:223], v[196:199], v[16:19]
	v_mfma_f32_16x16x32_bf16 v[8:11], v[212:215], v[204:207], v[8:11]
	v_mfma_f32_16x16x32_bf16 v[4:7], v[220:223], v[204:207], v[4:7]
	s_setprio 0
	s_add_i32 s38, s38, 2
	s_add_u32 s12, s12, 0x100
	s_addc_u32 s13, s13, 0
	s_add_u32 s36, s36, 0x100
	s_addc_u32 s37, s37, 0
	s_cmp_gt_u32 s38, 13
	s_barrier
	s_cbranch_scc0 .LBB0_353
	v_lshl_or_b32 v140, s30, 8, v144
	v_ashrrev_i32_e32 v141, 31, v140
	v_lshl_add_u32 v150, s31, 8, v142
	v_lshl_add_u64 v[140:141], v[140:141], 1, s[44:45]
	v_mad_i64_i32 v[146:147], s[12:13], v150, s64, v[140:141]
	v_pk_add_f32 v[130:131], v[130:131], 0 op_sel_hi:[1,0]
	v_pk_add_f32 v[128:129], v[128:129], 0 op_sel_hi:[1,0]
	v_pk_add_f32 v[148:149], v[126:127], 0 op_sel_hi:[1,0]
	v_pk_add_f32 v[126:127], v[124:125], 0 op_sel_hi:[1,0]
	v_cvt_pk_bf16_f32 v124, v128, v129
	v_cvt_pk_bf16_f32 v125, v130, v131
	v_pk_add_f32 v[120:121], v[120:121], 0 op_sel_hi:[1,0]
	v_cvt_pk_bf16_f32 v126, v126, v127
	v_cvt_pk_bf16_f32 v127, v148, v149
	global_store_dwordx4 v[146:147], v[124:127], off sc0 sc1
	v_pk_add_f32 v[122:123], v[122:123], 0 op_sel_hi:[1,0]
	v_pk_add_f32 v[116:117], v[116:117], 0 op_sel_hi:[1,0]
	v_pk_add_f32 v[124:125], v[114:115], 0 op_sel_hi:[1,0]
	v_pk_add_f32 v[114:115], v[112:113], 0 op_sel_hi:[1,0]
	v_cvt_pk_bf16_f32 v112, v120, v121
	v_cvt_pk_bf16_f32 v113, v122, v123
	v_pk_add_f32 v[104:105], v[104:105], 0 op_sel_hi:[1,0]
	v_cvt_pk_bf16_f32 v114, v114, v115
	v_cvt_pk_bf16_f32 v115, v124, v125
	global_store_dwordx4 v[146:147], v[112:115], off offset:256 sc0 sc1
	v_pk_add_f32 v[106:107], v[106:107], 0 op_sel_hi:[1,0]
	v_pk_add_f32 v[100:101], v[100:101], 0 op_sel_hi:[1,0]
	v_or_b32_e32 v112, 16, v150
	v_mad_i64_i32 v[112:113], s[12:13], v112, s64, v[140:141]
	v_pk_add_f32 v[114:115], v[118:119], 0 op_sel_hi:[1,0]
	v_pk_add_f32 v[118:119], v[110:111], 0 op_sel_hi:[1,0]
	v_pk_add_f32 v[110:111], v[108:109], 0 op_sel_hi:[1,0]
	v_cvt_pk_bf16_f32 v108, v116, v117
	v_cvt_pk_bf16_f32 v109, v114, v115
	v_pk_add_f32 v[88:89], v[88:89], 0 op_sel_hi:[1,0]
	v_cvt_pk_bf16_f32 v110, v110, v111
	v_cvt_pk_bf16_f32 v111, v118, v119
	global_store_dwordx4 v[112:113], v[108:111], off sc0 sc1
	v_pk_add_f32 v[90:91], v[90:91], 0 op_sel_hi:[1,0]
	v_pk_add_f32 v[84:85], v[84:85], 0 op_sel_hi:[1,0]
	v_pk_add_f32 v[108:109], v[98:99], 0 op_sel_hi:[1,0]
	v_pk_add_f32 v[98:99], v[96:97], 0 op_sel_hi:[1,0]
	v_cvt_pk_bf16_f32 v96, v104, v105
	v_cvt_pk_bf16_f32 v97, v106, v107
	v_pk_add_f32 v[72:73], v[72:73], 0 op_sel_hi:[1,0]
	v_cvt_pk_bf16_f32 v98, v98, v99
	v_cvt_pk_bf16_f32 v99, v108, v109
	global_store_dwordx4 v[112:113], v[96:99], off offset:256 sc0 sc1
	v_pk_add_f32 v[74:75], v[74:75], 0 op_sel_hi:[1,0]
	v_pk_add_f32 v[66:67], v[66:67], 0 op_sel_hi:[1,0]
	v_or_b32_e32 v96, 32, v150
	v_mad_i64_i32 v[96:97], s[12:13], v96, s64, v[140:141]
	v_pk_add_f32 v[98:99], v[102:103], 0 op_sel_hi:[1,0]
	v_pk_add_f32 v[102:103], v[94:95], 0 op_sel_hi:[1,0]
	v_pk_add_f32 v[94:95], v[92:93], 0 op_sel_hi:[1,0]
	v_cvt_pk_bf16_f32 v92, v100, v101
	v_cvt_pk_bf16_f32 v93, v98, v99
	v_pk_add_f32 v[64:65], v[64:65], 0 op_sel_hi:[1,0]
	v_cvt_pk_bf16_f32 v94, v94, v95
	v_cvt_pk_bf16_f32 v95, v102, v103
	global_store_dwordx4 v[96:97], v[92:95], off sc0 sc1
	v_pk_add_f32 v[56:57], v[56:57], 0 op_sel_hi:[1,0]
	v_pk_add_f32 v[58:59], v[58:59], 0 op_sel_hi:[1,0]
	v_pk_add_f32 v[92:93], v[82:83], 0 op_sel_hi:[1,0]
	v_pk_add_f32 v[82:83], v[80:81], 0 op_sel_hi:[1,0]
	v_cvt_pk_bf16_f32 v80, v88, v89
	v_cvt_pk_bf16_f32 v81, v90, v91
	v_pk_add_f32 v[52:53], v[52:53], 0 op_sel_hi:[1,0]
	v_cvt_pk_bf16_f32 v82, v82, v83
	v_cvt_pk_bf16_f32 v83, v92, v93
	global_store_dwordx4 v[96:97], v[80:83], off offset:256 sc0 sc1
	v_pk_add_f32 v[40:41], v[40:41], 0 op_sel_hi:[1,0]
	v_pk_add_f32 v[42:43], v[42:43], 0 op_sel_hi:[1,0]
	v_or_b32_e32 v80, 48, v150
	v_mad_i64_i32 v[80:81], s[12:13], v80, s64, v[140:141]
	v_pk_add_f32 v[82:83], v[86:87], 0 op_sel_hi:[1,0]
	v_pk_add_f32 v[86:87], v[78:79], 0 op_sel_hi:[1,0]
	v_pk_add_f32 v[78:79], v[76:77], 0 op_sel_hi:[1,0]
	v_cvt_pk_bf16_f32 v76, v84, v85
	v_cvt_pk_bf16_f32 v77, v82, v83
	v_pk_add_f32 v[36:37], v[36:37], 0 op_sel_hi:[1,0]
	v_cvt_pk_bf16_f32 v78, v78, v79
	v_cvt_pk_bf16_f32 v79, v86, v87
	global_store_dwordx4 v[80:81], v[76:79], off sc0 sc1
	v_pk_add_f32 v[24:25], v[24:25], 0 op_sel_hi:[1,0]
	v_pk_add_f32 v[26:27], v[26:27], 0 op_sel_hi:[1,0]
	v_pk_add_f32 v[76:77], v[70:71], 0 op_sel_hi:[1,0]
	v_pk_add_f32 v[70:71], v[68:69], 0 op_sel_hi:[1,0]
	v_cvt_pk_bf16_f32 v68, v72, v73
	v_cvt_pk_bf16_f32 v69, v74, v75
	v_pk_add_f32 v[20:21], v[20:21], 0 op_sel_hi:[1,0]
	v_cvt_pk_bf16_f32 v70, v70, v71
	v_cvt_pk_bf16_f32 v71, v76, v77
	global_store_dwordx4 v[80:81], v[68:71], off offset:256 sc0 sc1
	s_and_b64 vcc, exec, s[6:7]
	s_mov_b32 s30, s2
	v_add_u32_e32 v68, 0x80, v150
	v_mad_i64_i32 v[68:69], s[12:13], v68, s64, v[140:141]
	v_pk_add_f32 v[70:71], v[62:63], 0 op_sel_hi:[1,0]
	v_pk_add_f32 v[62:63], v[60:61], 0 op_sel_hi:[1,0]
	v_cvt_pk_bf16_f32 v60, v64, v65
	v_cvt_pk_bf16_f32 v61, v66, v67
	s_mov_b32 s31, s4
	v_cvt_pk_bf16_f32 v62, v62, v63
	v_cvt_pk_bf16_f32 v63, v70, v71
	global_store_dwordx4 v[68:69], v[60:63], off sc0 sc1
	s_mov_b64 s[14:15], s[10:11]
	v_pk_add_f32 v[10:11], v[10:11], 0 op_sel_hi:[1,0]
	v_pk_add_f32 v[60:61], v[50:51], 0 op_sel_hi:[1,0]
	v_pk_add_f32 v[50:51], v[48:49], 0 op_sel_hi:[1,0]
	v_cvt_pk_bf16_f32 v48, v56, v57
	v_cvt_pk_bf16_f32 v49, v58, v59
	v_pk_add_f32 v[8:9], v[8:9], 0 op_sel_hi:[1,0]
	v_cvt_pk_bf16_f32 v50, v50, v51
	v_cvt_pk_bf16_f32 v51, v60, v61
	global_store_dwordx4 v[68:69], v[48:51], off offset:256 sc0 sc1
	s_nop 1
	v_add_u32_e32 v48, 0x90, v150
	v_mad_i64_i32 v[48:49], s[12:13], v48, s64, v[140:141]
	v_pk_add_f32 v[50:51], v[54:55], 0 op_sel_hi:[1,0]
	v_pk_add_f32 v[54:55], v[46:47], 0 op_sel_hi:[1,0]
	v_pk_add_f32 v[46:47], v[44:45], 0 op_sel_hi:[1,0]
	v_cvt_pk_bf16_f32 v44, v52, v53
	v_cvt_pk_bf16_f32 v45, v50, v51
	s_nop 0
	v_cvt_pk_bf16_f32 v46, v46, v47
	v_cvt_pk_bf16_f32 v47, v54, v55
	global_store_dwordx4 v[48:49], v[44:47], off sc0 sc1
	s_nop 1
	v_pk_add_f32 v[44:45], v[34:35], 0 op_sel_hi:[1,0]
	v_pk_add_f32 v[34:35], v[32:33], 0 op_sel_hi:[1,0]
	v_cvt_pk_bf16_f32 v32, v40, v41
	v_cvt_pk_bf16_f32 v33, v42, v43
	s_nop 0
	v_cvt_pk_bf16_f32 v34, v34, v35
	v_cvt_pk_bf16_f32 v35, v44, v45
	global_store_dwordx4 v[48:49], v[32:35], off offset:256 sc0 sc1
	s_nop 1
	v_add_u32_e32 v32, 0xa0, v150
	v_mad_i64_i32 v[32:33], s[12:13], v32, s64, v[140:141]
	v_pk_add_f32 v[34:35], v[38:39], 0 op_sel_hi:[1,0]
	v_pk_add_f32 v[38:39], v[30:31], 0 op_sel_hi:[1,0]
	v_pk_add_f32 v[30:31], v[28:29], 0 op_sel_hi:[1,0]
	v_cvt_pk_bf16_f32 v28, v36, v37
	v_cvt_pk_bf16_f32 v29, v34, v35
	s_nop 0
	v_cvt_pk_bf16_f32 v30, v30, v31
	v_cvt_pk_bf16_f32 v31, v38, v39
	global_store_dwordx4 v[32:33], v[28:31], off sc0 sc1
	s_nop 1
	v_pk_add_f32 v[28:29], v[18:19], 0 op_sel_hi:[1,0]
	v_pk_add_f32 v[18:19], v[16:17], 0 op_sel_hi:[1,0]
	v_cvt_pk_bf16_f32 v16, v24, v25
	v_cvt_pk_bf16_f32 v17, v26, v27
	s_nop 0
	v_cvt_pk_bf16_f32 v18, v18, v19
	v_cvt_pk_bf16_f32 v19, v28, v29
	global_store_dwordx4 v[32:33], v[16:19], off offset:256 sc0 sc1
	s_nop 1
	v_add_u32_e32 v16, 0xb0, v150
	v_mad_i64_i32 v[16:17], s[12:13], v16, s64, v[140:141]
	v_pk_add_f32 v[18:19], v[22:23], 0 op_sel_hi:[1,0]
	v_pk_add_f32 v[22:23], v[14:15], 0 op_sel_hi:[1,0]
	v_pk_add_f32 v[14:15], v[12:13], 0 op_sel_hi:[1,0]
	v_cvt_pk_bf16_f32 v12, v20, v21
	v_cvt_pk_bf16_f32 v13, v18, v19
	s_mov_b64 s[12:13], s[8:9]
	v_cvt_pk_bf16_f32 v14, v14, v15
	v_cvt_pk_bf16_f32 v15, v22, v23
	global_store_dwordx4 v[16:17], v[12:15], off sc0 sc1
	s_nop 1
	v_pk_add_f32 v[12:13], v[6:7], 0 op_sel_hi:[1,0]
	v_pk_add_f32 v[6:7], v[4:5], 0 op_sel_hi:[1,0]
	v_cvt_pk_bf16_f32 v4, v8, v9
	v_cvt_pk_bf16_f32 v5, v10, v11
	s_nop 0
	v_cvt_pk_bf16_f32 v6, v6, v7
	v_cvt_pk_bf16_f32 v7, v12, v13
	global_store_dwordx4 v[16:17], v[4:7], off offset:256 sc0 sc1
	s_cbranch_vccz .LBB0_350
	s_waitcnt vmcnt(0)
	s_cmpk_gt_u32 s18, 0xff
	s_cbranch_scc1 .LBB0_357
	s_barrier
